# attention tile-range: eight ds_read_b128 issued together replace 32 serialized ds_read_b32; stacked
# baseline (speedup 1.0000x reference)
;     ...
;     if (SKIP_T > 0) {
;         float qa2 = 0.f, qb2 = 0.f, da = 3.0e38f, db = 3.0e38f;
;         { const float* wall = (const float*)(shm + LDS_WS);
; #pragma unroll
;           for (int w = 0; w < NW; ++w) { qa2 = fmaxf(qa2, wall[w * 128 + 0]); qb2 = fmaxf(qb2, wall[w * 128 + 1]); da = fminf(da, wall[w * 128 + 2]); db = fminf(db, wall[w * 128 + 3]); } }
;         const int kt0 = lane * KVBLK; const int dmin = kt0 + KVBLK - 1 < q0 ? q0 - (kt0 + KVBLK - 1) : (kt0 > q0 + QB - 1 ? kt0 - (q0 + QB - 1) : 0);
;         const float pen = sl * (float)dmin - (float)SKIP_T;
;         const bool needed = dmin == 0 || !(sqrtf(qa2 * ka2) * 1.01f - pen <= da) || !(sqrtf(qb2 * kb2) * 1.01f - pen <= db);
;         const unsigned long long mask = __ballot(needed);
;         const int tR = 63 - __clzll((long long)mask), tL = __ffsll((long long)mask) - 1;
.LBB0_326:
	s_waitcnt lgkmcnt(0)
	s_barrier
	v_lshlrev_b32_e32 v68, 6, v167
	v_or_b32_e32 v69, 63, v68
	s_or_b32 s15, s21, 0xff
	v_cmp_gt_u32_e32 vcc, s21, v69
	v_sub_u32_e32 v69, s21, v69
	v_sub_u32_e64 v68, v68, s15 clamp
	v_cndmask_b32_e32 v68, v68, v69, vcc
	v_cmp_ne_u32_e32 vcc, 0, v68
	s_mov_b64 s[36:37], -1
	s_and_saveexec_b64 s[58:59], vcc
	s_cbranch_execz .LBB0_330
	v_cvt_f32_u32_e32 v68, v68
	v_mov_b32_e32 v90, 0x10000
	ds_read_b128 v[74:77], v90
	ds_read_b128 v[78:81], v90 offset:512
	ds_read_b128 v[82:85], v90 offset:1024
	ds_read_b128 v[86:89], v90 offset:1536
	ds_read_b128 v[106:109], v90 offset:2048
	ds_read_b128 v[110:113], v90 offset:2560
	ds_read_b128 v[114:117], v90 offset:3072
	ds_read_b128 v[118:121], v90 offset:3584
	v_fmaak_f32 v68, v92, v68, 0xc2100000
	s_mov_b32 s8, 0x7f61b1e6
	s_waitcnt lgkmcnt(0)
	v_min3_f32 v69, v76, s8, v80
	v_min3_f32 v69, v69, v84, v88
	v_min3_f32 v69, v69, v108, v112
	v_min3_f32 v69, v69, v116, v120
	v_max3_f32 v70, v74, 0, v78
	v_max3_f32 v70, v70, v82, v86
	v_max3_f32 v70, v70, v106, v110
	v_max3_f32 v70, v70, v114, v118
	s_mov_b32 s8, 0xf800000
	v_mul_f32_e32 v67, v70, v67
	v_cmp_gt_f32_e32 vcc, s8, v67
	v_mul_f32_e32 v70, 0x4f800000, v67
	s_mov_b32 s8, 0x3f8147ae
	v_cndmask_b32_e32 v67, v67, v70, vcc
	v_sqrt_f32_e32 v70, v67
	s_nop 0
	v_add_u32_e32 v71, -1, v70
	v_fma_f32 v72, -v71, v70, v67
	v_cmp_ge_f32_e64 s[42:43], 0, v72
	v_add_u32_e32 v72, 1, v70
	s_nop 0
	v_cndmask_b32_e64 v71, v70, v71, s[42:43]
	v_fma_f32 v70, -v72, v70, v67
	v_cmp_lt_f32_e64 s[42:43], 0, v70
	s_nop 1
	v_cndmask_b32_e64 v70, v71, v72, s[42:43]
	v_mul_f32_e32 v71, 0x37800000, v70
	v_cndmask_b32_e32 v70, v70, v71, vcc
	v_mov_b32_e32 v71, 0x260
	v_cmp_class_f32_e32 vcc, v67, v71
	s_nop 1
	v_cndmask_b32_e32 v67, v70, v67, vcc
	v_fma_f32 v67, v67, s8, -v68
	v_cmp_le_f32_e32 vcc, v67, v69
	s_and_saveexec_b64 s[64:65], vcc
	s_cbranch_execz .LBB0_329
	v_max3_f32 v67, v75, 0, v79
	v_max3_f32 v67, v67, v83, v87
	v_max3_f32 v67, v67, v107, v111
	v_max3_f32 v67, v67, v115, v119
	s_mov_b32 s8, 0xf800000
	v_mul_f32_e32 v66, v67, v66
	v_cmp_gt_f32_e32 vcc, s8, v66
	v_mul_f32_e32 v67, 0x4f800000, v66
	s_mov_b32 s8, 0x3f8147ae
	v_cndmask_b32_e32 v66, v66, v67, vcc
	v_sqrt_f32_e32 v67, v66
	s_nop 0
	v_add_u32_e32 v69, -1, v67
	v_fma_f32 v70, -v69, v67, v66
	v_cmp_ge_f32_e64 s[42:43], 0, v70
	v_add_u32_e32 v70, 1, v67
	s_nop 0
	v_cndmask_b32_e64 v69, v67, v69, s[42:43]
	v_fma_f32 v67, -v70, v67, v66
	v_cmp_lt_f32_e64 s[42:43], 0, v67
	s_nop 1
	v_cndmask_b32_e64 v67, v69, v70, s[42:43]
	v_mul_f32_e32 v69, 0x37800000, v67
	v_cndmask_b32_e32 v67, v67, v69, vcc
	v_mov_b32_e32 v69, 0x260
	v_cmp_class_f32_e32 vcc, v66, v69
	s_nop 1
	v_cndmask_b32_e32 v66, v67, v66, vcc
	v_fma_f32 v66, v66, s8, -v68
	s_mov_b32 s8, 0x7f61b1e6
	v_min3_f32 v67, v77, s8, v81
	v_min3_f32 v67, v67, v85, v89
	v_min3_f32 v67, v67, v109, v113
	v_min3_f32 v67, v67, v117, v121
	v_cmp_nle_f32_e32 vcc, v66, v67
	s_orn2_b64 s[36:37], vcc, exec
